# attention step split into softmax | barrier | PV+QK with the two sub-head halves one barrier out of phase
# baseline (speedup 1.0000x reference)
.LBB0_201:
	s_or_b64 exec, exec, s[6:7]
	v_mov_b32_e32 v0, s97
	s_waitcnt lgkmcnt(0)
	s_barrier
	ds_read_b32 v0, v0
	s_movk_i32 s6, 0x17f
	s_waitcnt lgkmcnt(0)
	s_barrier
	v_cmp_lt_u32_e32 vcc, s6, v0
	v_readfirstlane_b32 s4, v0
	s_mov_b64 s[6:7], -1
	s_cbranch_vccnz .LBB0_196
	s_add_i32 s4, s4, s26
	s_and_b32 s6, s4, 0xffff
	s_mul_i32 s6, s6, 0xaaab
	s_lshr_b32 s8, s6, 20
	s_mul_i32 s6, s8, 24
	s_sub_i32 s9, s4, s6
	s_mul_i32 s4, s9, 0xab
	s_lshl_b32 s7, s8, 7
	s_bfe_u32 s4, s4, 0x6000a
	v_subrev_u32_e32 v26, s7, v199
	s_mul_i32 s6, s4, 6
	v_add_u32_e32 v212, 0xf80, v26
	s_sub_i32 s6, s9, s6
	v_or_b32_e32 v213, v212, v181
	s_lshl_b32 s7, s4, 12
	v_add_lshl_u32 v160, v213, s7, 11
	s_and_b32 s10, s6, 0xff
	v_lshl_add_u64 v[0:1], s[64:65], 0, v[160:161]
	s_lshl_b32 s4, s10, 8
	v_lshl_add_u64 v[0:1], v[0:1], 0, s[4:5]
	v_lshl_add_u64 v[0:1], v[176:177], 1, v[0:1]
	v_mov_b32_e32 v189, v161
	v_lshl_add_u64 v[24:25], v[0:1], 0, v[188:189]
	v_add_u32_e32 v2, s7, v200
	v_mov_b64_e32 v[0:1], s[30:31]
	v_mad_i64_i32 v[0:1], s[6:7], v2, s35, v[0:1]
	v_lshl_add_u64 v[0:1], v[0:1], 0, s[4:5]
	s_lshl_b32 s4, s9, 7
	v_mov_b32_e32 v191, v161
	s_and_b32 s4, s4, 0xff80
	v_lshl_add_u64 v[194:195], v[0:1], 0, v[190:191]
	v_lshl_add_u64 v[0:1], s[4:5], 0, v[178:179]
	s_mov_b32 s4, 0xc000
	v_lshlrev_b64 v[0:1], 13, v[0:1]
	v_add_co_u32_e32 v8, vcc, s4, v194
	v_lshl_add_u64 v[196:197], v[182:183], 0, v[0:1]
	s_nop 0
	v_addc_co_u32_e32 v9, vcc, 0, v195, vcc
	s_mov_b32 s4, 0x80000
	v_add_co_u32_e32 v12, vcc, s4, v196
	s_mov_b32 s4, 0x18000
	s_nop 0
	v_addc_co_u32_e32 v13, vcc, 0, v197, vcc
	global_load_dwordx4 v[0:3], v[194:195], off
	global_load_dwordx4 v[4:7], v[196:197], off
	s_nop 0
	global_load_dwordx4 v[8:11], v[8:9], off
	s_nop 0
	global_load_dwordx4 v[12:15], v[12:13], off
	v_add_co_u32_e32 v16, vcc, s4, v194
	s_mov_b32 s4, 0x24000
	s_nop 0
	v_addc_co_u32_e32 v17, vcc, 0, v195, vcc
	v_add_co_u32_e32 v20, vcc, s4, v194
	s_mov_b32 s24, 1
	s_nop 0
	v_addc_co_u32_e32 v21, vcc, 0, v195, vcc
	global_load_dwordx4 v[16:19], v[16:17], off
	s_nop 0
	global_load_dwordx4 v[20:23], v[20:21], off
	s_nop 0
	global_load_dwordx4 v[128:131], v[24:25], off
	global_load_dwordx4 v[132:135], v[24:25], off offset:32
	global_load_dwordx4 v[136:139], v[24:25], off offset:64
	global_load_dwordx4 v[140:143], v[24:25], off offset:96
	v_add_u32_e32 v189, 0xc800, v211
	v_add_u32_e32 v191, 0xf000, v211
	s_lshl_b32 s27, s10, 7
	s_lshl_b32 s22, s8, 1
	s_waitcnt vmcnt(9)
	ds_write_b128 v175, v[0:3]
	s_waitcnt vmcnt(7)
	ds_write_b128 v175, v[8:11] offset:8704
	ds_write2_b64 v189, v[4:5], v[6:7] offset0:128 offset1:130
	s_waitcnt vmcnt(6)
	ds_write2_b64 v191, v[12:13], v[14:15] offset1:2
	s_waitcnt vmcnt(5)
	ds_write_b128 v175, v[16:19] offset:17408
	s_waitcnt vmcnt(4)
	ds_write_b128 v175, v[20:23] offset:26112
	s_waitcnt lgkmcnt(0)
	s_barrier
	s_setprio 1
	v_add_u32_e32 v8, v203, v204
	ds_read_b128 v[0:3], v8
	ds_read_b128 v[4:7], v8 offset:32
	s_mov_b32 s4, s5
	s_mov_b32 s6, s5
	s_mov_b32 s7, s5
	s_waitcnt vmcnt(3) lgkmcnt(1)
	v_mfma_f32_32x32x16_bf16 v[64:79], v[0:3], v[128:131], 0
	s_mov_b32 s8, s5
	s_mov_b32 s9, s5
	s_mov_b32 s10, s5
	s_mov_b32 s11, s5
	s_mov_b32 s12, s5
	s_mov_b32 s13, s5
	s_mov_b32 s14, s5
	s_waitcnt vmcnt(2) lgkmcnt(0)
	v_mfma_f32_32x32x16_bf16 v[64:79], v[4:7], v[132:135], v[64:79]
	ds_read_b128 v[0:3], v8 offset:64
	ds_read_b128 v[4:7], v8 offset:96
	s_mov_b32 s15, s5
	s_mov_b32 s16, s5
	s_mov_b32 s17, s5
	s_mov_b32 s18, s5
	s_mov_b32 s19, s5
	s_waitcnt vmcnt(1) lgkmcnt(1)
	v_mfma_f32_32x32x16_bf16 v[64:79], v[0:3], v[136:139], v[64:79]
	s_waitcnt vmcnt(0) lgkmcnt(0)
	v_mfma_f32_32x32x16_bf16 v[64:79], v[4:7], v[140:143], v[64:79]
	ds_read_b128 v[0:3], v8 offset:8704
	ds_read_b128 v[4:7], v8 offset:8736
	ds_read_b128 v[16:19], v8 offset:8800
	s_waitcnt lgkmcnt(2)
	v_mfma_f32_32x32x16_bf16 v[80:95], v[0:3], v[128:131], 0
	ds_read_b128 v[0:3], v8 offset:8768
	s_waitcnt lgkmcnt(2)
	v_mfma_f32_32x32x16_bf16 v[80:95], v[4:7], v[132:135], v[80:95]
	s_waitcnt lgkmcnt(0)
	v_mfma_f32_32x32x16_bf16 v[80:95], v[0:3], v[136:139], v[80:95]
	v_mov_b64_e32 v[0:1], s[4:5]
	v_mov_b64_e32 v[2:3], s[6:7]
	v_mov_b64_e32 v[4:5], s[8:9]
	v_mov_b64_e32 v[6:7], s[10:11]
	v_mov_b64_e32 v[8:9], s[12:13]
	v_mov_b64_e32 v[10:11], s[14:15]
	v_mov_b64_e32 v[12:13], s[16:17]
	v_mfma_f32_32x32x16_bf16 v[80:95], v[16:19], v[140:143], v[80:95]
	v_mov_b64_e32 v[14:15], s[18:19]
	s_sub_i32 s12, 64, s22
	s_setprio 0
	v_add_u32_e32 v214, 0xf9f, v26
	v_mov_b64_e32 v[30:31], v[14:15]
	v_mov_b64_e32 v[46:47], v[14:15]
	v_mov_b64_e32 v[62:63], v[14:15]
	s_mov_b32 s13, 63
	s_sub_i32 s14, 63, s22
	s_mov_b32 s16, 2
	v_mov_b32_e32 v170, 0xff800000
	v_mov_b32_e32 v215, 0
	s_mov_b32 s15, 3
	v_mov_b64_e32 v[28:29], v[12:13]
	v_mov_b64_e32 v[26:27], v[10:11]
	v_mov_b64_e32 v[24:25], v[8:9]
	v_mov_b64_e32 v[22:23], v[6:7]
	v_mov_b64_e32 v[20:21], v[4:5]
	v_mov_b64_e32 v[18:19], v[2:3]
	v_mov_b64_e32 v[16:17], v[0:1]
	v_mov_b64_e32 v[44:45], v[12:13]
	v_mov_b64_e32 v[42:43], v[10:11]
	v_mov_b64_e32 v[40:41], v[8:9]
	v_mov_b64_e32 v[38:39], v[6:7]
	v_mov_b64_e32 v[36:37], v[4:5]
	v_mov_b64_e32 v[34:35], v[2:3]
	v_mov_b64_e32 v[32:33], v[0:1]
	v_mov_b64_e32 v[60:61], v[12:13]
	v_mov_b64_e32 v[58:59], v[10:11]
	v_mov_b64_e32 v[56:57], v[8:9]
	v_mov_b64_e32 v[54:55], v[6:7]
	v_mov_b64_e32 v[52:53], v[4:5]
	v_mov_b64_e32 v[50:51], v[2:3]
	v_mov_b64_e32 v[48:49], v[0:1]
	s_and_b64 vcc, exec, s[38:39]
	s_cbranch_vccz .Lda_nb0
	s_barrier
.Lda_nb0:
.LBB0_205:
	s_add_i32 s17, s15, -1
	s_cmp_lt_u32 s17, s12
	s_cselect_b64 s[6:7], -1, 0
	s_and_b64 s[8:9], s[6:7], exec
	s_cselect_b32 s4, s17, s14
	s_lshl_b32 s4, s4, 6
	s_add_i32 s18, s15, -2
	s_or_b32 s19, s4, 32
	s_cmp_lt_u32 s18, s12
	s_cselect_b64 s[8:9], -1, 0
	v_mad_u64_u32 v[144:145], s[10:11], s4, v228, v[194:195]
	v_mad_u64_u32 v[148:149], s[10:11], s19, v228, v[194:195]
	s_and_b64 s[10:11], s[8:9], exec
	s_cselect_b32 s10, s18, s14
	s_lshl_b32 s10, s10, 6
	s_mov_b32 s11, s5
	v_lshl_add_u64 v[152:153], s[10:11], 1, v[196:197]
	v_add_co_u32_e32 v154, vcc, 0x80000, v152
	global_load_dwordx4 v[144:147], v[144:145], off
	s_nop 0
	global_load_dwordx4 v[148:151], v[148:149], off
	v_addc_co_u32_e32 v155, vcc, 0, v153, vcc
	global_load_dwordx4 v[156:159], v[152:153], off
	s_nop 0
	global_load_dwordx4 v[152:155], v[154:155], off
	s_sub_i32 s10, s13, 30
	v_cmp_le_u32_e32 vcc, s10, v212
	s_and_b64 s[98:99], s[8:9], vcc
	s_sub_i32 s8, s13, 63
	v_cmp_le_u32_e32 vcc, s8, v214
	s_and_saveexec_b64 s[8:9], vcc
	s_cbranch_execz .Lda_sm0
	v_cmp_gt_u32_e32 vcc, s13, v212
	s_and_saveexec_b64 s[10:11], vcc
	s_cbranch_execz .LBB0_210
	v_add_u32_e32 v162, s13, v180
	v_subrev_u32_e32 v163, 63, v162
	v_cmp_le_u32_e32 vcc, v163, v213
	s_nop 1
	v_cndmask_b32_e32 v64, v229, v64, vcc
	v_cmp_lt_u32_e32 vcc, v163, v213
	v_subrev_u32_e32 v163, 61, v162
	s_nop 0
	v_cndmask_b32_e32 v65, v229, v65, vcc
	v_cmp_le_u32_e32 vcc, v163, v213
	v_subrev_u32_e32 v163, 60, v162
	s_nop 0
	v_cndmask_b32_e32 v66, v229, v66, vcc
	v_cmp_le_u32_e32 vcc, v163, v213
	v_subrev_u32_e32 v163, 55, v162
	s_nop 0
	v_cndmask_b32_e32 v67, v229, v67, vcc
	v_cmp_le_u32_e32 vcc, v163, v213
	v_subrev_u32_e32 v163, 54, v162
	s_nop 0
	v_cndmask_b32_e32 v68, v229, v68, vcc
	v_cmp_le_u32_e32 vcc, v163, v213
	v_subrev_u32_e32 v163, 53, v162
	s_nop 0
	v_cndmask_b32_e32 v69, v229, v69, vcc
	v_cmp_le_u32_e32 vcc, v163, v213
	v_subrev_u32_e32 v163, 52, v162
	s_nop 0
	v_cndmask_b32_e32 v70, v229, v70, vcc
	v_cmp_le_u32_e32 vcc, v163, v213
	v_subrev_u32_e32 v163, 47, v162
	s_nop 0
	v_cndmask_b32_e32 v71, v229, v71, vcc
	v_cmp_le_u32_e32 vcc, v163, v213
	v_subrev_u32_e32 v163, 46, v162
	s_nop 0
	v_cndmask_b32_e32 v72, v229, v72, vcc
	v_cmp_le_u32_e32 vcc, v163, v213
	v_subrev_u32_e32 v163, 45, v162
	s_nop 0
	v_cndmask_b32_e32 v73, v229, v73, vcc
	v_cmp_le_u32_e32 vcc, v163, v213
	v_subrev_u32_e32 v163, 44, v162
	s_nop 0
	v_cndmask_b32_e32 v74, v229, v74, vcc
	v_cmp_le_u32_e32 vcc, v163, v213
	v_subrev_u32_e32 v163, 39, v162
	s_nop 0
	v_cndmask_b32_e32 v75, v229, v75, vcc
	v_cmp_le_u32_e32 vcc, v163, v213
	v_subrev_u32_e32 v163, 38, v162
	s_nop 0
	v_cndmask_b32_e32 v76, v229, v76, vcc
	v_cmp_le_u32_e32 vcc, v163, v213
	v_subrev_u32_e32 v163, 37, v162
	s_nop 0
	v_cndmask_b32_e32 v77, v229, v77, vcc
	v_cmp_le_u32_e32 vcc, v163, v213
	v_subrev_u32_e32 v163, 36, v162
	s_nop 0
	v_cndmask_b32_e32 v78, v229, v78, vcc
	v_cmp_le_u32_e32 vcc, v163, v213
	v_subrev_u32_e32 v163, 31, v162
	s_nop 0
	v_cndmask_b32_e32 v79, v229, v79, vcc
	v_cmp_le_u32_e32 vcc, v163, v213
	v_subrev_u32_e32 v163, 30, v162
	s_nop 0
	v_cndmask_b32_e32 v80, v229, v80, vcc
	v_cmp_le_u32_e32 vcc, v163, v213
	v_subrev_u32_e32 v163, 29, v162
	s_nop 0
	v_cndmask_b32_e32 v81, v229, v81, vcc
	v_cmp_le_u32_e32 vcc, v163, v213
	v_subrev_u32_e32 v163, 28, v162
	s_nop 0
	v_cndmask_b32_e32 v82, v229, v82, vcc
	v_cmp_le_u32_e32 vcc, v163, v213
	v_subrev_u32_e32 v163, 23, v162
	s_nop 0
	v_cndmask_b32_e32 v83, v229, v83, vcc
	v_cmp_le_u32_e32 vcc, v163, v213
	v_subrev_u32_e32 v163, 22, v162
	s_nop 0
	v_cndmask_b32_e32 v84, v229, v84, vcc
	v_cmp_le_u32_e32 vcc, v163, v213
	v_subrev_u32_e32 v163, 21, v162
	s_nop 0
	v_cndmask_b32_e32 v85, v229, v85, vcc
	v_cmp_le_u32_e32 vcc, v163, v213
	v_subrev_u32_e32 v163, 20, v162
	s_nop 0
	v_cndmask_b32_e32 v86, v229, v86, vcc
	v_cmp_le_u32_e32 vcc, v163, v213
	v_add_u32_e32 v163, -15, v162
	s_nop 0
	v_cndmask_b32_e32 v87, v229, v87, vcc
	v_cmp_le_u32_e32 vcc, v163, v213
	v_add_u32_e32 v163, -14, v162
	s_nop 0
	v_cndmask_b32_e32 v88, v229, v88, vcc
	v_cmp_le_u32_e32 vcc, v163, v213
	v_add_u32_e32 v163, -13, v162
	s_nop 0
	v_cndmask_b32_e32 v89, v229, v89, vcc
	v_cmp_le_u32_e32 vcc, v163, v213
	v_add_u32_e32 v163, -12, v162
	s_nop 0
	v_cndmask_b32_e32 v90, v229, v90, vcc
	v_cmp_le_u32_e32 vcc, v163, v213
	v_add_u32_e32 v163, -7, v162
	s_nop 0
	v_cndmask_b32_e32 v91, v229, v91, vcc
	v_cmp_le_u32_e32 vcc, v163, v213
	v_add_u32_e32 v163, -6, v162
	s_nop 0
	v_cndmask_b32_e32 v92, v229, v92, vcc
	v_cmp_le_u32_e32 vcc, v163, v213
	v_add_u32_e32 v163, -5, v162
	v_add_u32_e32 v162, -4, v162
	v_cndmask_b32_e32 v93, v229, v93, vcc
	v_cmp_le_u32_e32 vcc, v163, v213
	s_nop 1
	v_cndmask_b32_e32 v94, v229, v94, vcc
	v_cmp_le_u32_e32 vcc, v162, v213
	s_nop 1
	v_cndmask_b32_e32 v95, v229, v95, vcc

.LBB0_212:
	v_sub_f32_e32 v71, v71, v234
	v_sub_f32_e32 v70, v70, v234
	v_sub_f32_e32 v69, v69, v234
	v_sub_f32_e32 v68, v68, v234
	v_sub_f32_e32 v67, v67, v234
	v_sub_f32_e32 v66, v66, v234
	v_sub_f32_e32 v65, v65, v234
	v_sub_f32_e32 v64, v64, v234
	v_sub_f32_e32 v87, v87, v234
	v_sub_f32_e32 v86, v86, v234
	v_sub_f32_e32 v85, v85, v234
	v_sub_f32_e32 v84, v84, v234
	v_sub_f32_e32 v83, v83, v234
	v_sub_f32_e32 v82, v82, v234
	v_sub_f32_e32 v81, v81, v234
	v_sub_f32_e32 v80, v80, v234
	v_sub_f32_e32 v75, v75, v234
	v_sub_f32_e32 v74, v74, v234
	v_sub_f32_e32 v73, v73, v234
	v_sub_f32_e32 v72, v72, v234
	v_sub_f32_e32 v91, v91, v234
	v_sub_f32_e32 v90, v90, v234
	v_sub_f32_e32 v89, v89, v234
	v_sub_f32_e32 v88, v88, v234
	v_exp_f32_e32 v64, v64
	v_exp_f32_e32 v65, v65
	v_exp_f32_e32 v66, v66
	v_exp_f32_e32 v67, v67
	v_exp_f32_e32 v68, v68
	v_exp_f32_e32 v69, v69
	v_exp_f32_e32 v70, v70
	v_exp_f32_e32 v71, v71
	v_exp_f32_e32 v80, v80
	v_exp_f32_e32 v81, v81
	v_exp_f32_e32 v82, v82
	v_exp_f32_e32 v83, v83
	v_exp_f32_e32 v84, v84
	v_exp_f32_e32 v85, v85
	v_exp_f32_e32 v86, v86
	v_exp_f32_e32 v87, v87
	v_sub_f32_e32 v79, v79, v234
	v_sub_f32_e32 v78, v78, v234
	v_sub_f32_e32 v77, v77, v234
	v_sub_f32_e32 v76, v76, v234
	v_sub_f32_e32 v95, v95, v234
	v_sub_f32_e32 v94, v94, v234
	v_sub_f32_e32 v93, v93, v234
	v_sub_f32_e32 v92, v92, v234
	v_exp_f32_e32 v72, v72
	v_exp_f32_e32 v73, v73
	v_exp_f32_e32 v74, v74
	v_exp_f32_e32 v75, v75
	v_exp_f32_e32 v88, v88
	v_exp_f32_e32 v90, v90
	v_exp_f32_e32 v91, v91
	v_exp_f32_e32 v89, v89
	v_exp_f32_e32 v76, v76
	v_exp_f32_e32 v77, v77
	v_exp_f32_e32 v78, v78
	v_exp_f32_e32 v79, v79
	v_exp_f32_e32 v92, v92
	v_exp_f32_e32 v93, v93
	v_exp_f32_e32 v94, v94
	v_exp_f32_e32 v95, v95
	v_pk_add_f32 v[226:227], v[68:69], v[84:85]
	v_pk_add_f32 v[236:237], v[64:65], v[80:81]
	v_pk_add_f32 v[238:239], v[70:71], v[86:87]
	v_pk_add_f32 v[240:241], v[66:67], v[82:83]
	v_pk_add_f32 v[222:223], v[74:75], v[90:91]
	v_pk_add_f32 v[224:225], v[72:73], v[88:89]
	v_pk_add_f32 v[238:239], v[240:241], v[238:239]
	v_pk_add_f32 v[226:227], v[236:237], v[226:227]
	v_pk_add_f32 v[162:163], v[76:77], v[92:93]
	v_pk_add_f32 v[164:165], v[78:79], v[94:95]
	v_pk_add_f32 v[224:225], v[224:225], v[226:227]
	v_pk_add_f32 v[222:223], v[222:223], v[238:239]
	v_pk_add_f32 v[162:163], v[162:163], v[224:225]
	v_pk_add_f32 v[164:165], v[164:165], v[222:223]
	v_add_f32_e32 v162, v162, v163
	v_add_f32_e32 v163, v164, v165
	v_add_f32_e32 v162, v162, v163
	v_fmac_f32_e32 v162, v215, v170
	v_mov_b32_e32 v170, v234
	v_mov_b32_e32 v215, v162
.Lda_sm0:
	s_or_b64 exec, exec, s[8:9]
	s_barrier
	s_sub_i32 s8, s13, 63
	v_cmp_le_u32_e32 vcc, s8, v214
	s_and_saveexec_b64 s[8:9], vcc
	s_cbranch_execz .LBB0_213
	s_setprio 1
	v_add_u32_e32 v163, v202, v169
	ds_read_b128 v[222:225], v163 offset:52224
	ds_read_b128 v[240:243], v163 offset:56832
	ds_read_b128 v[244:247], v163 offset:61440
	ds_read_b128 v[248:251], v207 offset:52224
	v_cvt_pk_bf16_f32 v236, v64, v65
	v_cvt_pk_bf16_f32 v237, v66, v67
	v_cvt_pk_bf16_f32 v238, v68, v69
	v_cvt_pk_bf16_f32 v239, v70, v71
	s_waitcnt lgkmcnt(3)
	s_nop 0
	v_mfma_f32_32x32x16_bf16 v[48:63], v[222:225], v[236:239], v[48:63]
	ds_read_b128 v[222:225], v163 offset:52256
	s_waitcnt lgkmcnt(3)
	v_mfma_f32_32x32x16_bf16 v[32:47], v[240:243], v[236:239], v[32:47]
	ds_read_b128 v[240:243], v163 offset:56864
	s_waitcnt lgkmcnt(3)
	v_mfma_f32_32x32x16_bf16 v[16:31], v[244:247], v[236:239], v[16:31]
	ds_read_b128 v[244:247], v163 offset:61472
	s_waitcnt lgkmcnt(3)
	v_mfma_f32_32x32x16_bf16 v[0:15], v[248:251], v[236:239], v[0:15]
	ds_read_b128 v[248:251], v207 offset:52256
	v_cvt_pk_bf16_f32 v236, v72, v73
	v_cvt_pk_bf16_f32 v237, v74, v75
	v_cvt_pk_bf16_f32 v238, v76, v77
	v_cvt_pk_bf16_f32 v239, v78, v79
	s_waitcnt lgkmcnt(3)
	s_nop 0
	v_mfma_f32_32x32x16_bf16 v[48:63], v[222:225], v[236:239], v[48:63]
	ds_read_b128 v[222:225], v163 offset:52288
	s_waitcnt lgkmcnt(3)
	v_mfma_f32_32x32x16_bf16 v[32:47], v[240:243], v[236:239], v[32:47]
	ds_read_b128 v[240:243], v163 offset:56896
	s_waitcnt lgkmcnt(3)
	v_mfma_f32_32x32x16_bf16 v[16:31], v[244:247], v[236:239], v[16:31]
	ds_read_b128 v[244:247], v163 offset:61504
	s_waitcnt lgkmcnt(3)
	v_mfma_f32_32x32x16_bf16 v[0:15], v[248:251], v[236:239], v[0:15]
	ds_read_b128 v[248:251], v207 offset:52288
	v_cvt_pk_bf16_f32 v236, v80, v81
	v_cvt_pk_bf16_f32 v237, v82, v83
	v_cvt_pk_bf16_f32 v238, v84, v85
	v_cvt_pk_bf16_f32 v239, v86, v87
	s_waitcnt lgkmcnt(3)
	s_nop 0
	v_mfma_f32_32x32x16_bf16 v[48:63], v[222:225], v[236:239], v[48:63]
	ds_read_b128 v[222:225], v163 offset:52320
	s_waitcnt lgkmcnt(3)
	v_mfma_f32_32x32x16_bf16 v[32:47], v[240:243], v[236:239], v[32:47]
	ds_read_b128 v[240:243], v163 offset:56928
	s_waitcnt lgkmcnt(3)
	v_mfma_f32_32x32x16_bf16 v[16:31], v[244:247], v[236:239], v[16:31]
	ds_read_b128 v[244:247], v163 offset:61536
	s_waitcnt lgkmcnt(3)
	v_mfma_f32_32x32x16_bf16 v[0:15], v[248:251], v[236:239], v[0:15]
	ds_read_b128 v[248:251], v207 offset:52320
	v_cvt_pk_bf16_f32 v236, v88, v89
	v_cvt_pk_bf16_f32 v237, v90, v91
	v_cvt_pk_bf16_f32 v238, v92, v93
	v_cvt_pk_bf16_f32 v239, v94, v95
	s_waitcnt lgkmcnt(3)
	s_nop 0
	v_mfma_f32_32x32x16_bf16 v[48:63], v[222:225], v[236:239], v[48:63]
	s_waitcnt lgkmcnt(2)
	v_mfma_f32_32x32x16_bf16 v[32:47], v[240:243], v[236:239], v[32:47]
	s_waitcnt lgkmcnt(1)
	v_mfma_f32_32x32x16_bf16 v[16:31], v[244:247], v[236:239], v[16:31]
	s_waitcnt lgkmcnt(0)
	v_mfma_f32_32x32x16_bf16 v[0:15], v[248:251], v[236:239], v[0:15]
	s_setprio 0
.LBB0_213:
	s_or_b64 exec, exec, s[8:9]
	s_and_saveexec_b64 s[8:9], s[98:99]
	s_cbranch_execz .LBB0_207
	s_mul_i32 s10, s24, 0x4400
	s_setprio 1
	v_add3_u32 v162, v203, s10, v204
	ds_read_b128 v[112:115], v162
	ds_read_b128 v[116:119], v162 offset:32
	ds_read_b128 v[120:123], v162 offset:64
	ds_read_b128 v[124:127], v162 offset:96
	ds_read_b128 v[222:225], v162 offset:8704
	ds_read_b128 v[236:239], v162 offset:8736
	ds_read_b128 v[240:243], v162 offset:8768
	ds_read_b128 v[244:247], v162 offset:8800
	s_waitcnt lgkmcnt(7)
	v_mfma_f32_32x32x16_bf16 v[96:111], v[112:115], v[128:131], 0
	s_waitcnt lgkmcnt(6)
	v_mfma_f32_32x32x16_bf16 v[96:111], v[116:119], v[132:135], v[96:111]
	s_waitcnt lgkmcnt(5)
	v_mfma_f32_32x32x16_bf16 v[96:111], v[120:123], v[136:139], v[96:111]
	s_waitcnt lgkmcnt(4)
	v_mfma_f32_32x32x16_bf16 v[96:111], v[124:127], v[140:143], v[96:111]
	s_waitcnt lgkmcnt(3)
	v_mfma_f32_32x32x16_bf16 v[112:127], v[222:225], v[128:131], 0
	s_waitcnt lgkmcnt(2)
	v_mfma_f32_32x32x16_bf16 v[112:127], v[236:239], v[132:135], v[112:127]
	s_waitcnt lgkmcnt(1)
	v_mfma_f32_32x32x16_bf16 v[112:127], v[240:243], v[136:139], v[112:127]
	s_waitcnt lgkmcnt(0)
	v_mfma_f32_32x32x16_bf16 v[112:127], v[244:247], v[140:143], v[112:127]
	s_setprio 0
.LBB0_207:
	s_or_b64 exec, exec, s[8:9]
	s_mul_i32 s8, s16, 0x4400
	v_add_u32_e32 v162, s8, v175
	s_cmp_lt_u32 s15, s12
	s_waitcnt vmcnt(3)
	ds_write_b128 v162, v[144:147]
	s_waitcnt vmcnt(2)
	ds_write_b128 v162, v[148:151] offset:8704
	s_waitcnt vmcnt(1)
	ds_write2_b64 v208, v[156:157], v[158:159] offset1:2
	v_add_u32_e32 v144, 0x2000, v208
	s_cselect_b32 s9, s15, s14
	s_waitcnt vmcnt(0)
	ds_write2_b64 v144, v[152:153], v[154:155] offset0:128 offset1:130
	s_lshl_b32 s9, s9, 6
	v_lshl_add_u64 v[152:153], s[4:5], 1, v[196:197]
	v_mad_u64_u32 v[144:145], s[10:11], s9, v228, v[194:195]
	s_or_b32 s9, s9, 32
	v_add_co_u32_e32 v154, vcc, 0x80000, v152
	v_mad_u64_u32 v[148:149], s[10:11], s9, v228, v[194:195]
	s_nop 0
	v_addc_co_u32_e32 v155, vcc, 0, v153, vcc
	s_waitcnt lgkmcnt(0)
	s_barrier
	global_load_dwordx4 v[144:147], v[144:145], off
	s_nop 0
	global_load_dwordx4 v[148:151], v[148:149], off
	s_nop 0
	global_load_dwordx4 v[156:159], v[152:153], off
	s_nop 0
	global_load_dwordx4 v[152:155], v[154:155], off
	s_add_i32 s4, s13, 34
	v_cmp_le_u32_e32 vcc, s4, v212
	s_and_b64 s[98:99], s[6:7], vcc
	s_add_i32 s4, s13, 1
	v_cmp_le_u32_e32 vcc, s4, v214
	s_and_saveexec_b64 s[6:7], vcc
	s_cbranch_execz .Lda_sm1
	s_add_i32 s4, s13, 64
	v_cmp_gt_u32_e32 vcc, s4, v212
	s_and_saveexec_b64 s[8:9], vcc
	s_cbranch_execz .LBB0_218
	v_add_u32_e32 v162, s13, v180
	v_add_u32_e32 v163, 1, v162
	v_cmp_lt_u32_e32 vcc, v163, v213
	s_nop 1
	v_cndmask_b32_e32 v97, v229, v97, vcc
	v_cmp_le_u32_e32 vcc, v163, v213
	v_add_u32_e32 v163, 3, v162
	s_nop 0
	v_cndmask_b32_e32 v96, v229, v96, vcc
	v_cmp_le_u32_e32 vcc, v163, v213
	v_add_u32_e32 v163, 4, v162
	s_nop 0
	v_cndmask_b32_e32 v98, v229, v98, vcc
	v_cmp_le_u32_e32 vcc, v163, v213
	v_add_u32_e32 v163, 9, v162
	s_nop 0
	v_cndmask_b32_e32 v99, v229, v99, vcc
	v_cmp_le_u32_e32 vcc, v163, v213
	v_add_u32_e32 v163, 10, v162
	s_nop 0
	v_cndmask_b32_e32 v100, v229, v100, vcc
	v_cmp_le_u32_e32 vcc, v163, v213
	v_add_u32_e32 v163, 11, v162
	s_nop 0
	v_cndmask_b32_e32 v101, v229, v101, vcc
	v_cmp_le_u32_e32 vcc, v163, v213
	v_add_u32_e32 v163, 12, v162
	s_nop 0
	v_cndmask_b32_e32 v102, v229, v102, vcc
	v_cmp_le_u32_e32 vcc, v163, v213
	v_add_u32_e32 v163, 17, v162
	s_nop 0
	v_cndmask_b32_e32 v103, v229, v103, vcc
	v_cmp_le_u32_e32 vcc, v163, v213
	v_add_u32_e32 v163, 18, v162
	s_nop 0
	v_cndmask_b32_e32 v104, v229, v104, vcc
	v_cmp_le_u32_e32 vcc, v163, v213
	v_add_u32_e32 v163, 19, v162
	s_nop 0
	v_cndmask_b32_e32 v105, v229, v105, vcc
	v_cmp_le_u32_e32 vcc, v163, v213
	v_add_u32_e32 v163, 20, v162
	s_nop 0
	v_cndmask_b32_e32 v106, v229, v106, vcc
	v_cmp_le_u32_e32 vcc, v163, v213
	v_add_u32_e32 v163, 25, v162
	s_nop 0
	v_cndmask_b32_e32 v107, v229, v107, vcc
	v_cmp_le_u32_e32 vcc, v163, v213
	v_add_u32_e32 v163, 26, v162
	s_nop 0
	v_cndmask_b32_e32 v108, v229, v108, vcc
	v_cmp_le_u32_e32 vcc, v163, v213
	v_add_u32_e32 v163, 27, v162
	s_nop 0
	v_cndmask_b32_e32 v109, v229, v109, vcc
	v_cmp_le_u32_e32 vcc, v163, v213
	v_add_u32_e32 v163, 28, v162
	s_nop 0
	v_cndmask_b32_e32 v110, v229, v110, vcc
	v_cmp_le_u32_e32 vcc, v163, v213
	v_add_u32_e32 v163, 33, v162
	s_nop 0
	v_cndmask_b32_e32 v111, v229, v111, vcc
	v_cmp_le_u32_e32 vcc, v163, v213
	v_add_u32_e32 v163, 34, v162
	s_nop 0
	v_cndmask_b32_e32 v112, v229, v112, vcc
	v_cmp_le_u32_e32 vcc, v163, v213
	v_add_u32_e32 v163, 35, v162
	s_nop 0
	v_cndmask_b32_e32 v113, v229, v113, vcc
	v_cmp_le_u32_e32 vcc, v163, v213
	v_add_u32_e32 v163, 36, v162
	s_nop 0
	v_cndmask_b32_e32 v114, v229, v114, vcc
	v_cmp_le_u32_e32 vcc, v163, v213
	v_add_u32_e32 v163, 41, v162
	s_nop 0
	v_cndmask_b32_e32 v115, v229, v115, vcc
	v_cmp_le_u32_e32 vcc, v163, v213
	v_add_u32_e32 v163, 42, v162
	s_nop 0
	v_cndmask_b32_e32 v116, v229, v116, vcc
	v_cmp_le_u32_e32 vcc, v163, v213
	v_add_u32_e32 v163, 43, v162
	s_nop 0
	v_cndmask_b32_e32 v117, v229, v117, vcc
	v_cmp_le_u32_e32 vcc, v163, v213
	v_add_u32_e32 v163, 44, v162
	s_nop 0
	v_cndmask_b32_e32 v118, v229, v118, vcc
	v_cmp_le_u32_e32 vcc, v163, v213
	v_add_u32_e32 v163, 49, v162
	s_nop 0
	v_cndmask_b32_e32 v119, v229, v119, vcc
	v_cmp_le_u32_e32 vcc, v163, v213
	v_add_u32_e32 v163, 50, v162
	s_nop 0
	v_cndmask_b32_e32 v120, v229, v120, vcc
	v_cmp_le_u32_e32 vcc, v163, v213
	v_add_u32_e32 v163, 51, v162
	s_nop 0
	v_cndmask_b32_e32 v121, v229, v121, vcc
	v_cmp_le_u32_e32 vcc, v163, v213
	v_add_u32_e32 v163, 52, v162
	s_nop 0
	v_cndmask_b32_e32 v122, v229, v122, vcc
	v_cmp_le_u32_e32 vcc, v163, v213
	v_add_u32_e32 v163, 57, v162
	s_nop 0
	v_cndmask_b32_e32 v123, v229, v123, vcc
	v_cmp_le_u32_e32 vcc, v163, v213
	v_add_u32_e32 v163, 58, v162
	s_nop 0
	v_cndmask_b32_e32 v124, v229, v124, vcc
	v_cmp_le_u32_e32 vcc, v163, v213
	v_add_u32_e32 v163, 59, v162
	v_add_u32_e32 v162, 60, v162
	v_cndmask_b32_e32 v125, v229, v125, vcc
	v_cmp_le_u32_e32 vcc, v163, v213
	s_nop 1
	v_cndmask_b32_e32 v126, v229, v126, vcc
	v_cmp_le_u32_e32 vcc, v162, v213
	s_nop 1
	v_cndmask_b32_e32 v127, v229, v127, vcc

.LBB0_203:
	v_sub_f32_e32 v103, v103, v234
	v_sub_f32_e32 v102, v102, v234
	v_sub_f32_e32 v101, v101, v234
	v_sub_f32_e32 v100, v100, v234
	v_sub_f32_e32 v99, v99, v234
	v_sub_f32_e32 v98, v98, v234
	v_sub_f32_e32 v97, v97, v234
	v_sub_f32_e32 v96, v96, v234
	v_sub_f32_e32 v119, v119, v234
	v_sub_f32_e32 v118, v118, v234
	v_sub_f32_e32 v117, v117, v234
	v_sub_f32_e32 v116, v116, v234
	v_sub_f32_e32 v115, v115, v234
	v_sub_f32_e32 v114, v114, v234
	v_sub_f32_e32 v113, v113, v234
	v_sub_f32_e32 v112, v112, v234
	v_sub_f32_e32 v107, v107, v234
	v_sub_f32_e32 v106, v106, v234
	v_sub_f32_e32 v105, v105, v234
	v_sub_f32_e32 v104, v104, v234
	v_sub_f32_e32 v123, v123, v234
	v_sub_f32_e32 v122, v122, v234
	v_sub_f32_e32 v121, v121, v234
	v_sub_f32_e32 v120, v120, v234
	v_exp_f32_e32 v96, v96
	v_exp_f32_e32 v97, v97
	v_exp_f32_e32 v98, v98
	v_exp_f32_e32 v99, v99
	v_exp_f32_e32 v100, v100
	v_exp_f32_e32 v101, v101
	v_exp_f32_e32 v102, v102
	v_exp_f32_e32 v103, v103
	v_exp_f32_e32 v112, v112
	v_exp_f32_e32 v113, v113
	v_exp_f32_e32 v114, v114
	v_exp_f32_e32 v115, v115
	v_exp_f32_e32 v116, v116
	v_exp_f32_e32 v117, v117
	v_exp_f32_e32 v118, v118
	v_exp_f32_e32 v119, v119
	v_sub_f32_e32 v111, v111, v234
	v_sub_f32_e32 v110, v110, v234
	v_sub_f32_e32 v109, v109, v234
	v_sub_f32_e32 v108, v108, v234
	v_sub_f32_e32 v127, v127, v234
	v_sub_f32_e32 v126, v126, v234
	v_sub_f32_e32 v125, v125, v234
	v_sub_f32_e32 v124, v124, v234
	v_exp_f32_e32 v104, v104
	v_exp_f32_e32 v105, v105
	v_exp_f32_e32 v106, v106
	v_exp_f32_e32 v107, v107
	v_exp_f32_e32 v120, v120
	v_exp_f32_e32 v122, v122
	v_exp_f32_e32 v123, v123
	v_exp_f32_e32 v121, v121
	v_exp_f32_e32 v108, v108
	v_exp_f32_e32 v109, v109
	v_exp_f32_e32 v110, v110
	v_exp_f32_e32 v111, v111
	v_exp_f32_e32 v124, v124
	v_exp_f32_e32 v125, v125
	v_exp_f32_e32 v126, v126
	v_exp_f32_e32 v127, v127
	v_pk_add_f32 v[226:227], v[100:101], v[116:117]
	v_pk_add_f32 v[236:237], v[96:97], v[112:113]
	v_pk_add_f32 v[238:239], v[102:103], v[118:119]
	v_pk_add_f32 v[240:241], v[98:99], v[114:115]
	v_pk_add_f32 v[222:223], v[106:107], v[122:123]
	v_pk_add_f32 v[224:225], v[104:105], v[120:121]
	v_pk_add_f32 v[238:239], v[240:241], v[238:239]
	v_pk_add_f32 v[226:227], v[236:237], v[226:227]
	v_pk_add_f32 v[162:163], v[108:109], v[124:125]
	v_pk_add_f32 v[164:165], v[110:111], v[126:127]
	v_pk_add_f32 v[224:225], v[224:225], v[226:227]
	v_pk_add_f32 v[222:223], v[222:223], v[238:239]
	v_pk_add_f32 v[162:163], v[162:163], v[224:225]
	v_pk_add_f32 v[164:165], v[164:165], v[222:223]
	v_add_f32_e32 v162, v162, v163
	v_add_f32_e32 v163, v164, v165
	v_add_f32_e32 v162, v162, v163
	v_fmac_f32_e32 v162, v215, v170
	v_mov_b32_e32 v170, v234
	v_mov_b32_e32 v215, v162
.Lda_sm1:
	s_or_b64 exec, exec, s[6:7]
	s_barrier
	s_add_i32 s4, s13, 1
	v_cmp_le_u32_e32 vcc, s4, v214
	s_and_saveexec_b64 s[6:7], vcc
	s_cbranch_execz .Lda_pv1
	s_setprio 1
	ds_read_b128 v[222:225], v209
	ds_read_b128 v[240:243], v209 offset:4608
	ds_read_b128 v[244:247], v209 offset:9216
	ds_read_b128 v[248:251], v209 offset:13824
	v_cvt_pk_bf16_f32 v236, v96, v97
	v_cvt_pk_bf16_f32 v237, v98, v99
	v_cvt_pk_bf16_f32 v238, v100, v101
	v_cvt_pk_bf16_f32 v239, v102, v103
	s_waitcnt lgkmcnt(3)
	s_nop 0
	v_mfma_f32_32x32x16_bf16 v[48:63], v[222:225], v[236:239], v[48:63]
	ds_read_b128 v[222:225], v209 offset:32
	s_waitcnt lgkmcnt(3)
	v_mfma_f32_32x32x16_bf16 v[32:47], v[240:243], v[236:239], v[32:47]
	ds_read_b128 v[240:243], v209 offset:4640
	s_waitcnt lgkmcnt(3)
	v_mfma_f32_32x32x16_bf16 v[16:31], v[244:247], v[236:239], v[16:31]
	ds_read_b128 v[244:247], v209 offset:9248
	s_waitcnt lgkmcnt(3)
	v_mfma_f32_32x32x16_bf16 v[0:15], v[248:251], v[236:239], v[0:15]
	ds_read_b128 v[248:251], v209 offset:13856
	v_cvt_pk_bf16_f32 v236, v104, v105
	v_cvt_pk_bf16_f32 v237, v106, v107
	v_cvt_pk_bf16_f32 v238, v108, v109
	v_cvt_pk_bf16_f32 v239, v110, v111
	s_waitcnt lgkmcnt(3)
	s_nop 0
	v_mfma_f32_32x32x16_bf16 v[48:63], v[222:225], v[236:239], v[48:63]
	ds_read_b128 v[222:225], v209 offset:64
	s_waitcnt lgkmcnt(3)
	v_mfma_f32_32x32x16_bf16 v[32:47], v[240:243], v[236:239], v[32:47]
	ds_read_b128 v[240:243], v209 offset:4672
	s_waitcnt lgkmcnt(3)
	v_mfma_f32_32x32x16_bf16 v[16:31], v[244:247], v[236:239], v[16:31]
	ds_read_b128 v[244:247], v209 offset:9280
	s_waitcnt lgkmcnt(3)
	v_mfma_f32_32x32x16_bf16 v[0:15], v[248:251], v[236:239], v[0:15]
	ds_read_b128 v[248:251], v209 offset:13888
	v_cvt_pk_bf16_f32 v236, v112, v113
	v_cvt_pk_bf16_f32 v237, v114, v115
	v_cvt_pk_bf16_f32 v238, v116, v117
	v_cvt_pk_bf16_f32 v239, v118, v119
	s_waitcnt lgkmcnt(3)
	s_nop 0
	v_mfma_f32_32x32x16_bf16 v[48:63], v[222:225], v[236:239], v[48:63]
	ds_read_b128 v[222:225], v209 offset:96
	s_waitcnt lgkmcnt(3)
	v_mfma_f32_32x32x16_bf16 v[32:47], v[240:243], v[236:239], v[32:47]
	ds_read_b128 v[240:243], v209 offset:4704
	s_waitcnt lgkmcnt(3)
	v_mfma_f32_32x32x16_bf16 v[16:31], v[244:247], v[236:239], v[16:31]
	ds_read_b128 v[244:247], v209 offset:9312
	s_waitcnt lgkmcnt(3)
	v_mfma_f32_32x32x16_bf16 v[0:15], v[248:251], v[236:239], v[0:15]
	ds_read_b128 v[248:251], v209 offset:13920
	v_cvt_pk_bf16_f32 v236, v120, v121
	v_cvt_pk_bf16_f32 v237, v122, v123
	v_cvt_pk_bf16_f32 v238, v124, v125
	v_cvt_pk_bf16_f32 v239, v126, v127
	s_waitcnt lgkmcnt(3)
	s_nop 0
	v_mfma_f32_32x32x16_bf16 v[48:63], v[222:225], v[236:239], v[48:63]
	s_waitcnt lgkmcnt(2)
	v_mfma_f32_32x32x16_bf16 v[32:47], v[240:243], v[236:239], v[32:47]
	s_waitcnt lgkmcnt(1)
	v_mfma_f32_32x32x16_bf16 v[16:31], v[244:247], v[236:239], v[16:31]
	s_waitcnt lgkmcnt(0)
	v_mfma_f32_32x32x16_bf16 v[0:15], v[248:251], v[236:239], v[0:15]
	s_setprio 0
.Lda_pv1:
	s_or_b64 exec, exec, s[6:7]
	s_and_saveexec_b64 s[6:7], s[98:99]
	s_cbranch_execz .LBB0_215
	s_mul_i32 s8, s16, 0x4400
	s_setprio 1
	v_add3_u32 v162, v203, s8, v204
	ds_read_b128 v[80:83], v162
	ds_read_b128 v[84:87], v162 offset:32
	ds_read_b128 v[88:91], v162 offset:64
	ds_read_b128 v[92:95], v162 offset:96
	ds_read_b128 v[222:225], v162 offset:8704
	ds_read_b128 v[236:239], v162 offset:8736
	ds_read_b128 v[240:243], v162 offset:8768
	ds_read_b128 v[244:247], v162 offset:8800
	s_waitcnt lgkmcnt(7)
	v_mfma_f32_32x32x16_bf16 v[64:79], v[80:83], v[128:131], 0
	s_waitcnt lgkmcnt(6)
	v_mfma_f32_32x32x16_bf16 v[64:79], v[84:87], v[132:135], v[64:79]
	s_waitcnt lgkmcnt(5)
	v_mfma_f32_32x32x16_bf16 v[64:79], v[88:91], v[136:139], v[64:79]
	s_waitcnt lgkmcnt(4)
	v_mfma_f32_32x32x16_bf16 v[64:79], v[92:95], v[140:143], v[64:79]
	s_waitcnt lgkmcnt(3)
	v_mfma_f32_32x32x16_bf16 v[80:95], v[222:225], v[128:131], 0
	s_waitcnt lgkmcnt(2)
	v_mfma_f32_32x32x16_bf16 v[80:95], v[236:239], v[132:135], v[80:95]
	s_waitcnt lgkmcnt(1)
	v_mfma_f32_32x32x16_bf16 v[80:95], v[240:243], v[136:139], v[80:95]
	s_waitcnt lgkmcnt(0)
	v_mfma_f32_32x32x16_bf16 v[80:95], v[244:247], v[140:143], v[80:95]
	s_setprio 0

.LBB0_204:
	s_add_i32 s4, s16, 1
	s_cmp_lg_u32 s16, 2
	s_cselect_b32 s24, s4, 0
	s_mul_i32 s4, s24, 0x4400
	v_add_u32_e32 v162, s4, v175
	s_add_i32 s4, s24, 1
	s_cmp_lg_u32 s24, 2
	s_cselect_b32 s16, s4, 0
	s_add_i32 s15, s15, 2
	s_addk_i32 s13, 0x80
	s_cmp_ge_u32 s17, s12
	s_waitcnt vmcnt(3)
	ds_write_b128 v162, v[144:147]
	s_waitcnt vmcnt(2)
	ds_write_b128 v162, v[148:151] offset:8704
	s_waitcnt vmcnt(1)
	ds_write2_b64 v189, v[156:157], v[158:159] offset0:128 offset1:130
	s_waitcnt vmcnt(0)
	ds_write2_b64 v191, v[152:153], v[154:155] offset1:2
	s_waitcnt lgkmcnt(0)
	s_barrier
	s_cbranch_scc0 .LBB0_205
.LBB0_220:
	s_and_b64 vcc, exec, s[40:41]
	s_cbranch_vccz .Lda_nb1
	s_barrier
